# GEMM K-loops: the duplicated back-to-back s_waitcnt lgkmcnt(0) at the head of 12 MFMA segments reduced to one
# speedup vs baseline: 1.0139x; 1.0047x over previous
; #define PG8_STAGE(bufoff, gbase, voff) do { _Pragma("unroll") for (int _i = 0; _i < 2; ++_i) \
;         __builtin_amdgcn_global_load_lds((const unsigned*)((const char*)(gbase) + (voff)[_i]), (LAS unsigned*)(lds + (bufoff) + ldsw + _i * 8192), 16, 0, 0); } while (0)
; #define PG8_LDA(dst, b, h) do { _Pragma("unroll") for (int m = 0; m < 4; ++m) _Pragma("unroll") for (int k = 0; k < 2; ++k) dst[m][k] = *(const LAS bf16x8*)(lds + PG8_SA(b, h) + aoff + m * 2048 + k * 1024); } while (0)
; #define PG8_LDB(dst, b, h) do { _Pragma("unroll") for (int n = 0; n < 2; ++n) _Pragma("unroll") for (int k = 0; k < 2; ++k) dst[n][k] = *(const LAS bf16x8*)(lds + PG8_SB(b, h) + boff + n * 2048 + k * 1024); } while (0)
; #define PG8_MMA(ai, bj, At, Bt) do { __builtin_amdgcn_s_setprio(1); _Pragma("unroll") for (int m = 0; m < 4; ++m) _Pragma("unroll") for (int n = 0; n < 2; ++n) _Pragma("unroll") for (int k = 0; k < 2; ++k) \
;         acc[ai][bj][m][n] = __builtin_amdgcn_mfma_f32_16x16x32_bf16(Bt[n][k], At[m][k], acc[ai][bj][m][n], 0, 0, 0); __builtin_amdgcn_s_setprio(0); } while (0)
; #define PG8_WAIT_V(n) asm volatile("s_waitcnt vmcnt(" #n ")" ::: "memory")
; #define PG8_WAIT_L(n) asm volatile("s_waitcnt lgkmcnt(" #n ")" ::: "memory")
; template <class Epi>
; __device__ __forceinline__ void gemm_phase(LAS unsigned char* lds, const Gemm g, const StaticOrder& S, const Epi& E) {
;     ...
;         for (int t = 0; t < nt; t += 2) {
;             const bool last = (t == nt - 2);
;             const char* a1 = cA + (size_t)(t + 1) * kstep;
;             const char* a2 = last ? nA : cA + (size_t)(t + 2) * kstep; const char* b2 = last ? nB : cB + (size_t)(t + 2) * kstep;
;             const char* a3 = a2 + kstep; const char* b3 = b2 + kstep;
;             PG8_LDB(B0, 0, 0); PG8_SCHED; PG8_LDA(At, 0, 0); PG8_STAGE(PG8_SA(1, 1), a1 + hstep, voffA);
;             PG8_WAIT_L(8); PG8_BAR; PG8_WAIT_L(0); PG8_MMA(0, 0, At, B0); PG8_BAR; PG8_SCHED;
;             PG8_LDB(B1, 0, 1); PG8_STAGE(PG8_SB(0, 0), b2, voffB);
;             PG8_BAR; PG8_WAIT_L(0); PG8_MMA(0, 1, At, B1); PG8_BAR;
;             PG8_LDA(At, 0, 1); PG8_STAGE(PG8_SA(0, 0), a2, voffA);
;             PG8_BAR; PG8_WAIT_L(0); PG8_MMA(1, 0, At, B0); PG8_BAR; PG8_SCHED;
;             PG8_STAGE(PG8_SB(0, 1), b2 + hstep, voffB);
;             PG8_WAIT_V(6); PG8_BAR; PG8_MMA(1, 1, At, B1); PG8_BAR;
.LBB0_80:
	ds_read_b128 v[154:157], v173
	ds_read_b128 v[176:179], v173 offset:1024
	ds_read_b128 v[180:183], v173 offset:2048
	ds_read_b128 v[184:187], v173 offset:3072
	s_add_u32 s26, s12, 0xfff80080
	s_addc_u32 s27, s13, -1
	s_cmp_eq_u32 s67, 28
	s_cselect_b32 s29, s7, s27
	s_cselect_b32 s28, s63, s26
	s_cselect_b32 s27, s25, s66
	s_cselect_b32 s26, s64, s65
	s_add_i32 m0, s42, 0xc000
	ds_read_b128 v[188:191], v174
	ds_read_b128 v[192:195], v174 offset:1024
	ds_read_b128 v[196:199], v174 offset:2048
	ds_read_b128 v[200:203], v174 offset:3072
	ds_read_b128 v[204:207], v174 offset:4096
	ds_read_b128 v[208:211], v174 offset:5120
	ds_read_b128 v[212:215], v174 offset:6144
	ds_read_b128 v[216:219], v174 offset:7168
	global_load_lds_dwordx4 v146, s[12:13]
	s_add_i32 m0, s42, 0xe000
	s_nop 0
	global_load_lds_dwordx4 v148, s[12:13]
	s_waitcnt lgkmcnt(8)
	s_barrier
	s_waitcnt lgkmcnt(0)
	v_mfma_f32_16x16x32_bf16 v[124:127], v[154:157], v[188:191], v[124:127]
	v_mfma_f32_16x16x32_bf16 v[120:123], v[180:183], v[188:191], v[120:123]
	v_mfma_f32_16x16x32_bf16 v[116:119], v[154:157], v[196:199], v[116:119]
	v_mfma_f32_16x16x32_bf16 v[112:115], v[180:183], v[196:199], v[112:115]
	v_mfma_f32_16x16x32_bf16 v[100:103], v[154:157], v[204:207], v[100:103]
	v_mfma_f32_16x16x32_bf16 v[96:99], v[180:183], v[204:207], v[96:99]
	v_mfma_f32_16x16x32_bf16 v[76:79], v[154:157], v[212:215], v[76:79]
	v_mfma_f32_16x16x32_bf16 v[72:75], v[180:183], v[212:215], v[72:75]
	v_mfma_f32_16x16x32_bf16 v[124:127], v[176:179], v[192:195], v[124:127]
	v_mfma_f32_16x16x32_bf16 v[120:123], v[184:187], v[192:195], v[120:123]
	v_mfma_f32_16x16x32_bf16 v[116:119], v[176:179], v[200:203], v[116:119]
	v_mfma_f32_16x16x32_bf16 v[112:115], v[184:187], v[200:203], v[112:115]
	v_mfma_f32_16x16x32_bf16 v[100:103], v[176:179], v[208:211], v[100:103]
	v_mfma_f32_16x16x32_bf16 v[96:99], v[184:187], v[208:211], v[96:99]
	v_mfma_f32_16x16x32_bf16 v[76:79], v[176:179], v[216:219], v[76:79]
	v_mfma_f32_16x16x32_bf16 v[72:75], v[184:187], v[216:219], v[72:75]
	s_barrier
	s_add_i32 s68, s55, s35
	s_add_u32 s72, s26, 0x80
	s_addc_u32 s73, s27, 0
	s_mov_b32 m0, s68
	ds_read_b128 v[220:223], v175
	ds_read_b128 v[224:227], v175 offset:1024
	ds_read_b128 v[228:231], v175 offset:2048
	ds_read_b128 v[232:235], v175 offset:3072
	global_load_lds_dwordx4 v140, s[26:27]
	s_add_i32 m0, s68, 0x2000
	s_nop 0
	global_load_lds_dwordx4 v136, s[26:27]
	s_barrier
	s_waitcnt lgkmcnt(0)
	v_mfma_f32_16x16x32_bf16 v[108:111], v[220:223], v[188:191], v[108:111]
	v_mfma_f32_16x16x32_bf16 v[104:107], v[228:231], v[188:191], v[104:107]
	v_mfma_f32_16x16x32_bf16 v[92:95], v[220:223], v[196:199], v[92:95]
	v_mfma_f32_16x16x32_bf16 v[88:91], v[228:231], v[196:199], v[88:91]
	v_mfma_f32_16x16x32_bf16 v[84:87], v[220:223], v[204:207], v[84:87]
	v_mfma_f32_16x16x32_bf16 v[80:83], v[228:231], v[204:207], v[80:83]
	v_mfma_f32_16x16x32_bf16 v[68:71], v[220:223], v[212:215], v[68:71]
	v_mfma_f32_16x16x32_bf16 v[64:67], v[228:231], v[212:215], v[64:67]
	v_mfma_f32_16x16x32_bf16 v[108:111], v[224:227], v[192:195], v[108:111]
	v_mfma_f32_16x16x32_bf16 v[104:107], v[232:235], v[192:195], v[104:107]
	v_mfma_f32_16x16x32_bf16 v[92:95], v[224:227], v[200:203], v[92:95]
	v_mfma_f32_16x16x32_bf16 v[88:91], v[232:235], v[200:203], v[88:91]
	v_mfma_f32_16x16x32_bf16 v[84:87], v[224:227], v[208:211], v[84:87]
	v_mfma_f32_16x16x32_bf16 v[80:83], v[232:235], v[208:211], v[80:83]
	v_mfma_f32_16x16x32_bf16 v[68:71], v[224:227], v[216:219], v[68:71]
	v_mfma_f32_16x16x32_bf16 v[64:67], v[232:235], v[216:219], v[64:67]
	s_mov_b32 m0, s42
	s_add_u32 s74, s28, 0x80
	s_addc_u32 s75, s29, 0
	s_barrier
	ds_read_b128 v[188:191], v174 offset:16384
	ds_read_b128 v[192:195], v174 offset:17408
	ds_read_b128 v[196:199], v174 offset:18432
	ds_read_b128 v[200:203], v174 offset:19456
	ds_read_b128 v[204:207], v174 offset:20480
	ds_read_b128 v[208:211], v174 offset:21504
	ds_read_b128 v[212:215], v174 offset:22528
	ds_read_b128 v[216:219], v174 offset:23552
	global_load_lds_dwordx4 v142, s[28:29]
	s_mov_b32 m0, s43
	s_nop 0
	global_load_lds_dwordx4 v138, s[28:29]
	s_barrier
	s_waitcnt lgkmcnt(0)
	v_mfma_f32_16x16x32_bf16 v[60:63], v[154:157], v[188:191], v[60:63]
	v_mfma_f32_16x16x32_bf16 v[56:59], v[180:183], v[188:191], v[56:59]
	v_mfma_f32_16x16x32_bf16 v[52:55], v[154:157], v[196:199], v[52:55]
	v_mfma_f32_16x16x32_bf16 v[48:51], v[180:183], v[196:199], v[48:51]
	v_mfma_f32_16x16x32_bf16 v[36:39], v[154:157], v[204:207], v[36:39]
	v_mfma_f32_16x16x32_bf16 v[32:35], v[180:183], v[204:207], v[32:35]
	v_mfma_f32_16x16x32_bf16 v[12:15], v[154:157], v[212:215], v[12:15]
	v_mfma_f32_16x16x32_bf16 v[8:11], v[180:183], v[212:215], v[8:11]
	v_mfma_f32_16x16x32_bf16 v[60:63], v[176:179], v[192:195], v[60:63]
	v_mfma_f32_16x16x32_bf16 v[56:59], v[184:187], v[192:195], v[56:59]
	v_mfma_f32_16x16x32_bf16 v[52:55], v[176:179], v[200:203], v[52:55]
	v_mfma_f32_16x16x32_bf16 v[48:51], v[184:187], v[200:203], v[48:51]
	v_mfma_f32_16x16x32_bf16 v[36:39], v[176:179], v[208:211], v[36:39]
	v_mfma_f32_16x16x32_bf16 v[32:35], v[184:187], v[208:211], v[32:35]
	v_mfma_f32_16x16x32_bf16 v[12:15], v[176:179], v[216:219], v[12:15]
	v_mfma_f32_16x16x32_bf16 v[8:11], v[184:187], v[216:219], v[8:11]
	s_barrier
	s_add_u32 s68, s26, 0x80000
	s_addc_u32 s69, s27, 0
	s_add_i32 s70, s56, s35
	s_mov_b32 m0, s70
	s_nop 0
	global_load_lds_dwordx4 v140, s[68:69]
	s_add_i32 m0, s70, 0x2000
	s_nop 0
	global_load_lds_dwordx4 v136, s[68:69]
	s_waitcnt vmcnt(6)
	s_barrier
; #define PG8_STAGE(bufoff, gbase, voff) do { _Pragma("unroll") for (int _i = 0; _i < 2; ++_i) \
;         __builtin_amdgcn_global_load_lds((const unsigned*)((const char*)(gbase) + (voff)[_i]), (LAS unsigned*)(lds + (bufoff) + ldsw + _i * 8192), 16, 0, 0); } while (0)
; #define PG8_LDA(dst, b, h) do { _Pragma("unroll") for (int m = 0; m < 4; ++m) _Pragma("unroll") for (int k = 0; k < 2; ++k) dst[m][k] = *(const LAS bf16x8*)(lds + PG8_SA(b, h) + aoff + m * 2048 + k * 1024); } while (0)
; #define PG8_LDB(dst, b, h) do { _Pragma("unroll") for (int n = 0; n < 2; ++n) _Pragma("unroll") for (int k = 0; k < 2; ++k) dst[n][k] = *(const LAS bf16x8*)(lds + PG8_SB(b, h) + boff + n * 2048 + k * 1024); } while (0)
; #define PG8_MMA(ai, bj, At, Bt) do { __builtin_amdgcn_s_setprio(1); _Pragma("unroll") for (int m = 0; m < 4; ++m) _Pragma("unroll") for (int n = 0; n < 2; ++n) _Pragma("unroll") for (int k = 0; k < 2; ++k) \
;         acc[ai][bj][m][n] = __builtin_amdgcn_mfma_f32_16x16x32_bf16(Bt[n][k], At[m][k], acc[ai][bj][m][n], 0, 0, 0); __builtin_amdgcn_s_setprio(0); } while (0)
; #define PG8_WAIT_V(n) asm volatile("s_waitcnt vmcnt(" #n ")" ::: "memory")
; #define PG8_WAIT_L(n) asm volatile("s_waitcnt lgkmcnt(" #n ")" ::: "memory")
; #define PG8_BAR __builtin_amdgcn_s_barrier()
; #define PG8_SCHED __builtin_amdgcn_sched_barrier(0)
; template <class Epi>
; __device__ __forceinline__ void gemm_phase(LAS unsigned char* lds, const Gemm g, const StaticOrder& S, const Epi& E) {
;     ...
;             PG8_BAR; PG8_WAIT_L(0); PG8_MMA(1, 0, At, B0); PG8_BAR; PG8_SCHED;
;             PG8_STAGE(PG8_SB(0, 1), b2 + hstep, voffB);
;             PG8_WAIT_V(6); PG8_BAR; PG8_MMA(1, 1, At, B1); PG8_BAR;
;             PG8_LDB(B0, 1, 0); PG8_SCHED; PG8_LDA(At, 1, 0); PG8_STAGE(PG8_SA(0, 1), a2 + hstep, voffA);
;             PG8_WAIT_L(8); PG8_BAR; PG8_WAIT_L(0); PG8_MMA(0, 0, At, B0); PG8_BAR; PG8_SCHED;
;             PG8_LDB(B1, 1, 1); PG8_STAGE(PG8_SB(1, 0), b3, voffB);
;             PG8_BAR; PG8_WAIT_L(0); PG8_MMA(0, 1, At, B1); PG8_BAR;
;             PG8_LDA(At, 1, 1); PG8_STAGE(PG8_SA(1, 0), a3, voffA);
;             PG8_BAR; PG8_WAIT_L(0); PG8_MMA(1, 0, At, B0); PG8_BAR; PG8_SCHED;
	v_mfma_f32_16x16x32_bf16 v[44:47], v[220:223], v[188:191], v[44:47]
	v_mfma_f32_16x16x32_bf16 v[40:43], v[228:231], v[188:191], v[40:43]
	v_mfma_f32_16x16x32_bf16 v[28:31], v[220:223], v[196:199], v[28:31]
	v_mfma_f32_16x16x32_bf16 v[24:27], v[228:231], v[196:199], v[24:27]
	v_mfma_f32_16x16x32_bf16 v[20:23], v[220:223], v[204:207], v[20:23]
	v_mfma_f32_16x16x32_bf16 v[16:19], v[228:231], v[204:207], v[16:19]
	v_mfma_f32_16x16x32_bf16 v[4:7], v[220:223], v[212:215], v[4:7]
	v_mfma_f32_16x16x32_bf16 v[0:3], v[228:231], v[212:215], v[0:3]
	v_mfma_f32_16x16x32_bf16 v[44:47], v[224:227], v[192:195], v[44:47]
	v_mfma_f32_16x16x32_bf16 v[40:43], v[232:235], v[192:195], v[40:43]
	v_mfma_f32_16x16x32_bf16 v[28:31], v[224:227], v[200:203], v[28:31]
	v_mfma_f32_16x16x32_bf16 v[24:27], v[232:235], v[200:203], v[24:27]
	v_mfma_f32_16x16x32_bf16 v[20:23], v[224:227], v[208:211], v[20:23]
	v_mfma_f32_16x16x32_bf16 v[16:19], v[232:235], v[208:211], v[16:19]
	v_mfma_f32_16x16x32_bf16 v[4:7], v[224:227], v[216:219], v[4:7]
	v_mfma_f32_16x16x32_bf16 v[0:3], v[232:235], v[216:219], v[0:3]
	s_add_i32 s68, 0, 0x18000
	s_barrier
	ds_read_b128 v[154:157], v236
	ds_read_b128 v[176:179], v236 offset:1024
	ds_read_b128 v[180:183], v236 offset:2048
	ds_read_b128 v[184:187], v236 offset:3072
	s_add_u32 s28, s28, 0x80000
	s_addc_u32 s29, s29, 0
	s_mov_b32 m0, s44
	ds_read_b128 v[188:191], v174 offset:32768
	ds_read_b128 v[192:195], v174 offset:33792
	ds_read_b128 v[196:199], v174 offset:34816
	ds_read_b128 v[200:203], v174 offset:35840
	ds_read_b128 v[204:207], v174 offset:36864
	ds_read_b128 v[208:211], v174 offset:37888
	ds_read_b128 v[212:215], v174 offset:38912
	ds_read_b128 v[216:219], v174 offset:39936
	global_load_lds_dwordx4 v142, s[28:29]
	s_mov_b32 m0, s45
	s_nop 0
	global_load_lds_dwordx4 v138, s[28:29]
	s_waitcnt lgkmcnt(8)
	s_barrier
	s_waitcnt lgkmcnt(0)
	v_mfma_f32_16x16x32_bf16 v[124:127], v[154:157], v[188:191], v[124:127]
	v_mfma_f32_16x16x32_bf16 v[120:123], v[180:183], v[188:191], v[120:123]
	v_mfma_f32_16x16x32_bf16 v[116:119], v[154:157], v[196:199], v[116:119]
	v_mfma_f32_16x16x32_bf16 v[112:115], v[180:183], v[196:199], v[112:115]
	v_mfma_f32_16x16x32_bf16 v[100:103], v[154:157], v[204:207], v[100:103]
	v_mfma_f32_16x16x32_bf16 v[96:99], v[180:183], v[204:207], v[96:99]
	v_mfma_f32_16x16x32_bf16 v[76:79], v[154:157], v[212:215], v[76:79]
	v_mfma_f32_16x16x32_bf16 v[72:75], v[180:183], v[212:215], v[72:75]
	v_mfma_f32_16x16x32_bf16 v[124:127], v[176:179], v[192:195], v[124:127]
	v_mfma_f32_16x16x32_bf16 v[120:123], v[184:187], v[192:195], v[120:123]
	v_mfma_f32_16x16x32_bf16 v[116:119], v[176:179], v[200:203], v[116:119]
	v_mfma_f32_16x16x32_bf16 v[112:115], v[184:187], v[200:203], v[112:115]
	v_mfma_f32_16x16x32_bf16 v[100:103], v[176:179], v[208:211], v[100:103]
	v_mfma_f32_16x16x32_bf16 v[96:99], v[184:187], v[208:211], v[96:99]
	v_mfma_f32_16x16x32_bf16 v[76:79], v[176:179], v[216:219], v[76:79]
	v_mfma_f32_16x16x32_bf16 v[72:75], v[184:187], v[216:219], v[72:75]
	s_barrier
	s_add_i32 s28, 0, 0x1c000
	s_add_i32 s29, s68, s35
	s_mov_b32 m0, s29
	ds_read_b128 v[220:223], v237
	ds_read_b128 v[224:227], v237 offset:1024
	ds_read_b128 v[228:231], v237 offset:2048
	ds_read_b128 v[232:235], v237 offset:3072
	global_load_lds_dwordx4 v140, s[72:73]
	s_add_i32 m0, s29, 0x2000
	s_nop 0
	global_load_lds_dwordx4 v136, s[72:73]
	s_barrier
	s_waitcnt lgkmcnt(0)
	v_mfma_f32_16x16x32_bf16 v[108:111], v[220:223], v[188:191], v[108:111]
	v_mfma_f32_16x16x32_bf16 v[104:107], v[228:231], v[188:191], v[104:107]
	v_mfma_f32_16x16x32_bf16 v[92:95], v[220:223], v[196:199], v[92:95]
	v_mfma_f32_16x16x32_bf16 v[88:91], v[228:231], v[196:199], v[88:91]
	v_mfma_f32_16x16x32_bf16 v[84:87], v[220:223], v[204:207], v[84:87]
	v_mfma_f32_16x16x32_bf16 v[80:83], v[228:231], v[204:207], v[80:83]
	v_mfma_f32_16x16x32_bf16 v[68:71], v[220:223], v[212:215], v[68:71]
	v_mfma_f32_16x16x32_bf16 v[64:67], v[228:231], v[212:215], v[64:67]
	v_mfma_f32_16x16x32_bf16 v[108:111], v[224:227], v[192:195], v[108:111]
	v_mfma_f32_16x16x32_bf16 v[104:107], v[232:235], v[192:195], v[104:107]
	v_mfma_f32_16x16x32_bf16 v[92:95], v[224:227], v[200:203], v[92:95]
	v_mfma_f32_16x16x32_bf16 v[88:91], v[232:235], v[200:203], v[88:91]
	v_mfma_f32_16x16x32_bf16 v[84:87], v[224:227], v[208:211], v[84:87]
	v_mfma_f32_16x16x32_bf16 v[80:83], v[232:235], v[208:211], v[80:83]
	v_mfma_f32_16x16x32_bf16 v[68:71], v[224:227], v[216:219], v[68:71]
	v_mfma_f32_16x16x32_bf16 v[64:67], v[232:235], v[216:219], v[64:67]
	s_mov_b32 m0, s48
	s_barrier
	ds_read_b128 v[188:191], v174 offset:49152
	ds_read_b128 v[192:195], v174 offset:50176
	ds_read_b128 v[196:199], v174 offset:51200
	ds_read_b128 v[200:203], v174 offset:52224
	ds_read_b128 v[204:207], v174 offset:53248
	ds_read_b128 v[208:211], v174 offset:54272
	ds_read_b128 v[212:215], v174 offset:55296
	ds_read_b128 v[216:219], v174 offset:56320
	global_load_lds_dwordx4 v142, s[74:75]
	s_mov_b32 m0, s49
	s_nop 0
	global_load_lds_dwordx4 v138, s[74:75]
	s_barrier
; __device__ __forceinline__ unsigned pk_bf16(float lo, float hi) { const f32x2 v = (f32x2){lo, hi}; const bf16v2 b = __builtin_convertvector(v, bf16v2); return __builtin_bit_cast(unsigned, b); }
; #define PG8_WAIT_V(n) asm volatile("s_waitcnt vmcnt(" #n ")" ::: "memory")
; #define PG8_WAIT_L(n) asm volatile("s_waitcnt lgkmcnt(" #n ")" ::: "memory")
; #define PG8_BAR __builtin_amdgcn_s_barrier()
; template <class Epi>
; __device__ __forceinline__ void gemm_phase(LAS unsigned char* lds, const Gemm g, const StaticOrder& S, const Epi& E) {
;     ...
;             PG8_WAIT_L(8); PG8_BAR; PG8_WAIT_L(0); PG8_MMA(0, 0, At, B0); PG8_BAR; PG8_SCHED;
;             PG8_LDB(B1, 1, 1); PG8_STAGE(PG8_SB(1, 0), b3, voffB);
;             PG8_BAR; PG8_WAIT_L(0); PG8_MMA(0, 1, At, B1); PG8_BAR;
;             PG8_LDA(At, 1, 1); PG8_STAGE(PG8_SA(1, 0), a3, voffA);
;             PG8_BAR; PG8_WAIT_L(0); PG8_MMA(1, 0, At, B0); PG8_BAR; PG8_SCHED;
;             PG8_STAGE(PG8_SB(1, 1), b3 + hstep, voffB);
;             PG8_WAIT_V(6); PG8_BAR; PG8_MMA(1, 1, At, B1); PG8_BAR;
;     __device__ __forceinline__ void operator()(const f32x4 (&acc)[2][2][4][2], const pg8::Unit& u, int wr, int wc, int fr, int fq) const {
;         const int row0 = u.pm * 256 + wr * 64 + fr, col0 = u.pn * 256 + wc * 32 + 8 * fq;
; #pragma unroll
;         for (int ai = 0; ai < 2; ++ai)
; #pragma unroll
;             for (int m = 0; m < 4; ++m) {
;                 const int row = row0 + ai * 128 + m * 16;
;                 bf16_t* rowp = Z + (size_t)row * LDZ + col0;
;                 const bool last = ((row & 63) == 63) && (row >= MP || (row & (SEQ - 1)) == SEQ - 1);
; #pragma unroll
;                 for (int bj = 0; bj < 2; ++bj) {
;                     const f32x4 v0 = acc[ai][bj][m][0], v1 = acc[ai][bj][m][1];
;                     u32x4 w; w.x = pk_bf16(v0[0], v0[1]); w.y = pk_bf16(v0[2], v0[3]); w.z = pk_bf16(v1[0], v1[1]); w.w = pk_bf16(v1[2], v1[3]);
;                     *(u32x4*)(rowp + bj * 128) = w;
;                     if (last) {
;                         const int c = col0 + bj * 128 - ZC_S;
;                         if (c >= 0 && c < NSHIFT) {
;                             float* o = row < MP ? out + O_SHP + (size_t)(row >> 13) * NSHIFT + c : out + O_SHS + (size_t)((row - MP) >> 6) * NSHIFT + c;
;                             *(f32x4*)o = v0; *(f32x4*)(o + 4) = v1;
;                         }
	s_waitcnt lgkmcnt(0)
	v_mfma_f32_16x16x32_bf16 v[60:63], v[154:157], v[188:191], v[60:63]
	v_mfma_f32_16x16x32_bf16 v[56:59], v[180:183], v[188:191], v[56:59]
	v_mfma_f32_16x16x32_bf16 v[52:55], v[154:157], v[196:199], v[52:55]
	v_mfma_f32_16x16x32_bf16 v[48:51], v[180:183], v[196:199], v[48:51]
	v_mfma_f32_16x16x32_bf16 v[36:39], v[154:157], v[204:207], v[36:39]
	v_mfma_f32_16x16x32_bf16 v[32:35], v[180:183], v[204:207], v[32:35]
	v_mfma_f32_16x16x32_bf16 v[12:15], v[154:157], v[212:215], v[12:15]
	v_mfma_f32_16x16x32_bf16 v[8:11], v[180:183], v[212:215], v[8:11]
	v_mfma_f32_16x16x32_bf16 v[60:63], v[176:179], v[192:195], v[60:63]
	v_mfma_f32_16x16x32_bf16 v[56:59], v[184:187], v[192:195], v[56:59]
	v_mfma_f32_16x16x32_bf16 v[52:55], v[176:179], v[200:203], v[52:55]
	v_mfma_f32_16x16x32_bf16 v[48:51], v[184:187], v[200:203], v[48:51]
	v_mfma_f32_16x16x32_bf16 v[36:39], v[176:179], v[208:211], v[36:39]
	v_mfma_f32_16x16x32_bf16 v[32:35], v[184:187], v[208:211], v[32:35]
	v_mfma_f32_16x16x32_bf16 v[12:15], v[176:179], v[216:219], v[12:15]
	v_mfma_f32_16x16x32_bf16 v[8:11], v[184:187], v[216:219], v[8:11]
	s_barrier
	s_add_u32 s26, s26, 0x80080
	s_addc_u32 s27, s27, 0
	s_add_i32 s28, s28, s35
	s_mov_b32 m0, s28
	s_nop 0
	global_load_lds_dwordx4 v140, s[26:27]
	s_add_i32 m0, s28, 0x2000
	s_nop 0
	global_load_lds_dwordx4 v136, s[26:27]
	s_waitcnt vmcnt(6)
	s_barrier
	v_mfma_f32_16x16x32_bf16 v[44:47], v[220:223], v[188:191], v[44:47]
	v_mfma_f32_16x16x32_bf16 v[40:43], v[228:231], v[188:191], v[40:43]
	v_mfma_f32_16x16x32_bf16 v[28:31], v[220:223], v[196:199], v[28:31]
	v_mfma_f32_16x16x32_bf16 v[24:27], v[228:231], v[196:199], v[24:27]
	v_mfma_f32_16x16x32_bf16 v[20:23], v[220:223], v[204:207], v[20:23]
	v_mfma_f32_16x16x32_bf16 v[16:19], v[228:231], v[204:207], v[16:19]
	v_mfma_f32_16x16x32_bf16 v[4:7], v[220:223], v[212:215], v[4:7]
	v_mfma_f32_16x16x32_bf16 v[0:3], v[228:231], v[212:215], v[0:3]
	v_mfma_f32_16x16x32_bf16 v[44:47], v[224:227], v[192:195], v[44:47]
	v_mfma_f32_16x16x32_bf16 v[40:43], v[232:235], v[192:195], v[40:43]
	v_mfma_f32_16x16x32_bf16 v[28:31], v[224:227], v[200:203], v[28:31]
	v_mfma_f32_16x16x32_bf16 v[24:27], v[232:235], v[200:203], v[24:27]
	v_mfma_f32_16x16x32_bf16 v[20:23], v[224:227], v[208:211], v[20:23]
	v_mfma_f32_16x16x32_bf16 v[16:19], v[232:235], v[208:211], v[16:19]
	v_mfma_f32_16x16x32_bf16 v[4:7], v[224:227], v[216:219], v[4:7]
	v_mfma_f32_16x16x32_bf16 v[0:3], v[232:235], v[216:219], v[0:3]
	s_add_i32 s67, s67, 2
	s_add_u32 s12, s12, 0x100
	s_addc_u32 s13, s13, 0
	s_add_u32 s65, s65, 0x100
	s_addc_u32 s66, s66, 0
	s_cmp_gt_u32 s67, 29
	s_barrier
	s_cbranch_scc0 .LBB0_80
	s_lshl_b32 s7, s31, 8
	s_add_i32 s7, s7, s47
	v_lshl_or_b32 v156, s30, 8, v172
	s_add_i32 s12, s7, 0xffff8000
	v_or_b32_e32 v176, s7, v161
	v_ashrrev_i32_e32 v157, 31, v156
	s_lshr_b32 s63, s12, 6
	s_ashr_i32 s12, s7, 13
	v_mov_b64_e32 v[178:179], s[14:15]
	s_mul_i32 s26, s12, 0xc80
	v_mad_i64_i32 v[180:181], s[12:13], v176, s58, v[178:179]
	v_lshlrev_b64 v[154:155], 1, v[156:157]
	v_cvt_pk_bf16_f32 v108, v108, v109
	v_cvt_pk_bf16_f32 v109, v110, v111
	v_cvt_pk_bf16_f32 v110, v104, v105
	v_or_b32_e32 v104, 16, v176
	v_cvt_pk_bf16_f32 v92, v92, v93
	v_cvt_pk_bf16_f32 v93, v94, v95
	v_cvt_pk_bf16_f32 v94, v88, v89
	v_or_b32_e32 v88, 32, v176
	v_cvt_pk_bf16_f32 v84, v84, v85
	v_cvt_pk_bf16_f32 v85, v86, v87
	v_cvt_pk_bf16_f32 v87, v82, v83
	v_or_b32_e32 v82, 48, v176
	v_lshl_add_u64 v[180:181], v[180:181], 0, v[154:155]
	v_cvt_pk_bf16_f32 v111, v106, v107
	v_mad_i64_i32 v[104:105], s[12:13], v104, s58, v[178:179]
	v_mad_i64_i32 v[88:89], s[12:13], v88, s58, v[178:179]
	v_cvt_pk_bf16_f32 v86, v80, v81
	v_mad_i64_i32 v[80:81], s[12:13], v82, s58, v[178:179]
	v_bitop3_b32 v83, v176, s60, 48 bitop3:0xc8
	global_store_dwordx4 v[180:181], v[108:111], off offset:256
	v_cvt_pk_bf16_f32 v95, v90, v91
	v_cmp_lt_i32_e32 vcc, s59, v82
	v_lshl_add_u64 v[108:109], v[104:105], 0, v[154:155]
	v_cmp_eq_u32_e64 s[12:13], s60, v83
	global_store_dwordx4 v[108:109], v[92:95], off offset:256
	s_or_b64 s[12:13], vcc, s[12:13]
	s_mul_hi_u32 s25, s63, 0x3200
	v_lshl_add_u64 v[92:93], v[88:89], 0, v[154:155]
	s_mulk_i32 s63, 0x3200
	s_ashr_i32 s27, s26, 31
	v_cvt_pk_bf16_f32 v124, v124, v125
	v_cvt_pk_bf16_f32 v125, v126, v127
	v_cvt_pk_bf16_f32 v126, v120, v121
	v_cvt_pk_bf16_f32 v127, v122, v123
	v_cvt_pk_bf16_f32 v104, v116, v117
	v_cvt_pk_bf16_f32 v105, v118, v119
	v_cvt_pk_bf16_f32 v106, v112, v113
	v_cvt_pk_bf16_f32 v107, v114, v115
	v_cvt_pk_bf16_f32 v88, v100, v101
	v_cvt_pk_bf16_f32 v89, v102, v103
	v_cvt_pk_bf16_f32 v90, v96, v97
	v_cvt_pk_bf16_f32 v91, v98, v99
	global_store_dwordx4 v[92:93], v[84:87], off offset:256
	v_lshl_add_u64 v[80:81], v[80:81], 0, v[154:155]
	s_and_b64 s[28:29], s[8:9], s[12:13]
	v_cmp_gt_i32_e32 vcc, s50, v82
	v_cvt_pk_bf16_f32 v82, v76, v77
	v_cvt_pk_bf16_f32 v83, v78, v79
	v_cvt_pk_bf16_f32 v84, v72, v73
	v_cvt_pk_bf16_f32 v85, v74, v75
	v_add_u32_e32 v144, 0xfffff400, v156
	global_store_dwordx4 v[180:181], v[124:127], off
	global_store_dwordx4 v[108:109], v[104:107], off
	global_store_dwordx4 v[92:93], v[88:91], off
	global_store_dwordx4 v[80:81], v[82:85], off
	s_and_saveexec_b64 s[30:31], s[28:29]
	s_cbranch_execz .LBB0_84
	v_cmp_gt_u32_e64 s[12:13], s57, v144
	s_and_b64 exec, exec, s[12:13]
	s_cbranch_execz .LBB0_84
	s_lshl_b64 s[12:13], s[26:27], 2
	s_add_u32 s12, s22, s12
	s_addc_u32 s13, s23, s13
	s_add_u32 s64, s51, s63
	s_addc_u32 s65, s52, s25
	v_mov_b32_e32 v82, s65
	v_mov_b32_e32 v83, s13
	v_cndmask_b32_e32 v83, v82, v83, vcc
	v_mov_b32_e32 v82, s64
	v_mov_b32_e32 v84, s12
	v_cndmask_b32_e32 v82, v82, v84, vcc
	v_lshl_add_u64 v[82:83], v[144:145], 2, v[82:83]
	global_store_dwordx4 v[82:83], v[76:79], off
	global_store_dwordx4 v[82:83], v[72:75], off offset:16

; #define PG8_STAGE(bufoff, gbase, voff) do { _Pragma("unroll") for (int _i = 0; _i < 2; ++_i) \
;         __builtin_amdgcn_global_load_lds((const unsigned*)((const char*)(gbase) + (voff)[_i]), (LAS unsigned*)(lds + (bufoff) + ldsw + _i * 8192), 16, 0, 0); } while (0)
; #define PG8_LDA(dst, b, h) do { _Pragma("unroll") for (int m = 0; m < 4; ++m) _Pragma("unroll") for (int k = 0; k < 2; ++k) dst[m][k] = *(const LAS bf16x8*)(lds + PG8_SA(b, h) + aoff + m * 2048 + k * 1024); } while (0)
; #define PG8_LDB(dst, b, h) do { _Pragma("unroll") for (int n = 0; n < 2; ++n) _Pragma("unroll") for (int k = 0; k < 2; ++k) dst[n][k] = *(const LAS bf16x8*)(lds + PG8_SB(b, h) + boff + n * 2048 + k * 1024); } while (0)
; #define PG8_MMA(ai, bj, At, Bt) do { __builtin_amdgcn_s_setprio(1); _Pragma("unroll") for (int m = 0; m < 4; ++m) _Pragma("unroll") for (int n = 0; n < 2; ++n) _Pragma("unroll") for (int k = 0; k < 2; ++k) \
;         acc[ai][bj][m][n] = __builtin_amdgcn_mfma_f32_16x16x32_bf16(Bt[n][k], At[m][k], acc[ai][bj][m][n], 0, 0, 0); __builtin_amdgcn_s_setprio(0); } while (0)
; #define PG8_WAIT_V(n) asm volatile("s_waitcnt vmcnt(" #n ")" ::: "memory")
; #define PG8_WAIT_L(n) asm volatile("s_waitcnt lgkmcnt(" #n ")" ::: "memory")
; template <class Epi>
; __device__ __forceinline__ void gemm_phase(LAS unsigned char* lds, const Gemm g, const StaticOrder& S, const Epi& E) {
;     ...
;         for (int t = 0; t < nt; t += 2) {
;             const bool last = (t == nt - 2);
;             const char* a1 = cA + (size_t)(t + 1) * kstep;
;             const char* a2 = last ? nA : cA + (size_t)(t + 2) * kstep; const char* b2 = last ? nB : cB + (size_t)(t + 2) * kstep;
;             const char* a3 = a2 + kstep; const char* b3 = b2 + kstep;
;             PG8_LDB(B0, 0, 0); PG8_SCHED; PG8_LDA(At, 0, 0); PG8_STAGE(PG8_SA(1, 1), a1 + hstep, voffA);
;             PG8_WAIT_L(8); PG8_BAR; PG8_WAIT_L(0); PG8_MMA(0, 0, At, B0); PG8_BAR; PG8_SCHED;
;             PG8_LDB(B1, 0, 1); PG8_STAGE(PG8_SB(0, 0), b2, voffB);
;             PG8_BAR; PG8_WAIT_L(0); PG8_MMA(0, 1, At, B1); PG8_BAR;
;             PG8_LDA(At, 0, 1); PG8_STAGE(PG8_SA(0, 0), a2, voffA);
;             PG8_BAR; PG8_WAIT_L(0); PG8_MMA(1, 0, At, B0); PG8_BAR; PG8_SCHED;
;             PG8_STAGE(PG8_SB(0, 1), b2 + hstep, voffB);
;             PG8_WAIT_V(6); PG8_BAR; PG8_MMA(1, 1, At, B1); PG8_BAR;
.LBB0_559:
	ds_read_b128 v[156:159], v133
	ds_read_b128 v[160:163], v133 offset:1024
	ds_read_b128 v[164:167], v133 offset:2048
	ds_read_b128 v[168:171], v133 offset:3072
	s_add_u32 s34, s30, 0xfff80080
	s_addc_u32 s35, s31, -1
	s_cmp_eq_u32 s65, 28
	s_cselect_b32 s41, s25, s35
	s_cselect_b32 s40, s61, s34
	s_cselect_b32 s35, s23, s64
	s_cselect_b32 s34, s62, s63
	s_add_i32 m0, s21, 0xc000
	ds_read_b128 v[172:175], v153
	ds_read_b128 v[176:179], v153 offset:1024
	ds_read_b128 v[180:183], v153 offset:2048
	ds_read_b128 v[184:187], v153 offset:3072
	ds_read_b128 v[188:191], v153 offset:4096
	ds_read_b128 v[192:195], v153 offset:5120
	ds_read_b128 v[196:199], v153 offset:6144
	ds_read_b128 v[200:203], v153 offset:7168
	global_load_lds_dwordx4 v142, s[30:31]
	s_add_i32 m0, s21, 0xe000
	s_nop 0
	global_load_lds_dwordx4 v144, s[30:31]
	s_waitcnt lgkmcnt(8)
	s_barrier
	s_waitcnt lgkmcnt(0)
	v_mfma_f32_16x16x32_bf16 v[124:127], v[156:159], v[172:175], v[124:127]
	v_mfma_f32_16x16x32_bf16 v[120:123], v[164:167], v[172:175], v[120:123]
	v_mfma_f32_16x16x32_bf16 v[116:119], v[156:159], v[180:183], v[116:119]
	v_mfma_f32_16x16x32_bf16 v[112:115], v[164:167], v[180:183], v[112:115]
	v_mfma_f32_16x16x32_bf16 v[100:103], v[156:159], v[188:191], v[100:103]
	v_mfma_f32_16x16x32_bf16 v[96:99], v[164:167], v[188:191], v[96:99]
	v_mfma_f32_16x16x32_bf16 v[84:87], v[156:159], v[196:199], v[84:87]
	v_mfma_f32_16x16x32_bf16 v[80:83], v[164:167], v[196:199], v[80:83]
	v_mfma_f32_16x16x32_bf16 v[124:127], v[160:163], v[176:179], v[124:127]
	v_mfma_f32_16x16x32_bf16 v[120:123], v[168:171], v[176:179], v[120:123]
	v_mfma_f32_16x16x32_bf16 v[116:119], v[160:163], v[184:187], v[116:119]
	v_mfma_f32_16x16x32_bf16 v[112:115], v[168:171], v[184:187], v[112:115]
	v_mfma_f32_16x16x32_bf16 v[100:103], v[160:163], v[192:195], v[100:103]
	v_mfma_f32_16x16x32_bf16 v[96:99], v[168:171], v[192:195], v[96:99]
	v_mfma_f32_16x16x32_bf16 v[84:87], v[160:163], v[200:203], v[84:87]
	v_mfma_f32_16x16x32_bf16 v[80:83], v[168:171], v[200:203], v[80:83]
	s_barrier
	s_add_i32 s66, s54, s43
	s_add_u32 s72, s34, 0x80
	s_addc_u32 s73, s35, 0
	s_mov_b32 m0, s66
	ds_read_b128 v[204:207], v154
	ds_read_b128 v[208:211], v154 offset:1024
	ds_read_b128 v[212:215], v154 offset:2048
	ds_read_b128 v[216:219], v154 offset:3072
	global_load_lds_dwordx4 v138, s[34:35]
	s_add_i32 m0, s66, 0x2000
	s_nop 0
	global_load_lds_dwordx4 v134, s[34:35]
	s_barrier
	s_waitcnt lgkmcnt(0)
	v_mfma_f32_16x16x32_bf16 v[108:111], v[204:207], v[172:175], v[108:111]
	v_mfma_f32_16x16x32_bf16 v[104:107], v[212:215], v[172:175], v[104:107]
	v_mfma_f32_16x16x32_bf16 v[92:95], v[204:207], v[180:183], v[92:95]
	v_mfma_f32_16x16x32_bf16 v[88:91], v[212:215], v[180:183], v[88:91]
	v_mfma_f32_16x16x32_bf16 v[76:79], v[204:207], v[188:191], v[76:79]
	v_mfma_f32_16x16x32_bf16 v[72:75], v[212:215], v[188:191], v[72:75]
	v_mfma_f32_16x16x32_bf16 v[68:71], v[204:207], v[196:199], v[68:71]
	v_mfma_f32_16x16x32_bf16 v[64:67], v[212:215], v[196:199], v[64:67]
	v_mfma_f32_16x16x32_bf16 v[108:111], v[208:211], v[176:179], v[108:111]
	v_mfma_f32_16x16x32_bf16 v[104:107], v[216:219], v[176:179], v[104:107]
	v_mfma_f32_16x16x32_bf16 v[92:95], v[208:211], v[184:187], v[92:95]
	v_mfma_f32_16x16x32_bf16 v[88:91], v[216:219], v[184:187], v[88:91]
	v_mfma_f32_16x16x32_bf16 v[76:79], v[208:211], v[192:195], v[76:79]
	v_mfma_f32_16x16x32_bf16 v[72:75], v[216:219], v[192:195], v[72:75]
	v_mfma_f32_16x16x32_bf16 v[68:71], v[208:211], v[200:203], v[68:71]
	v_mfma_f32_16x16x32_bf16 v[64:67], v[216:219], v[200:203], v[64:67]
	s_mov_b32 m0, s21
	s_add_u32 s74, s40, 0x80
	s_addc_u32 s75, s41, 0
	s_barrier
	ds_read_b128 v[172:175], v153 offset:16384
	ds_read_b128 v[176:179], v153 offset:17408
	ds_read_b128 v[180:183], v153 offset:18432
	ds_read_b128 v[184:187], v153 offset:19456
	ds_read_b128 v[188:191], v153 offset:20480
	ds_read_b128 v[192:195], v153 offset:21504
	ds_read_b128 v[196:199], v153 offset:22528
	ds_read_b128 v[200:203], v153 offset:23552
	global_load_lds_dwordx4 v140, s[40:41]
	s_mov_b32 m0, s46
	s_nop 0
	global_load_lds_dwordx4 v136, s[40:41]
	s_barrier
	s_waitcnt lgkmcnt(0)
	v_mfma_f32_16x16x32_bf16 v[60:63], v[156:159], v[172:175], v[60:63]
	v_mfma_f32_16x16x32_bf16 v[56:59], v[164:167], v[172:175], v[56:59]
	v_mfma_f32_16x16x32_bf16 v[52:55], v[156:159], v[180:183], v[52:55]
	v_mfma_f32_16x16x32_bf16 v[48:51], v[164:167], v[180:183], v[48:51]
	v_mfma_f32_16x16x32_bf16 v[36:39], v[156:159], v[188:191], v[36:39]
	v_mfma_f32_16x16x32_bf16 v[32:35], v[164:167], v[188:191], v[32:35]
	v_mfma_f32_16x16x32_bf16 v[20:23], v[156:159], v[196:199], v[20:23]
	v_mfma_f32_16x16x32_bf16 v[16:19], v[164:167], v[196:199], v[16:19]
	v_mfma_f32_16x16x32_bf16 v[60:63], v[160:163], v[176:179], v[60:63]
	v_mfma_f32_16x16x32_bf16 v[56:59], v[168:171], v[176:179], v[56:59]
	v_mfma_f32_16x16x32_bf16 v[52:55], v[160:163], v[184:187], v[52:55]
	v_mfma_f32_16x16x32_bf16 v[48:51], v[168:171], v[184:187], v[48:51]
	v_mfma_f32_16x16x32_bf16 v[36:39], v[160:163], v[192:195], v[36:39]
	v_mfma_f32_16x16x32_bf16 v[32:35], v[168:171], v[192:195], v[32:35]
	v_mfma_f32_16x16x32_bf16 v[20:23], v[160:163], v[200:203], v[20:23]
	v_mfma_f32_16x16x32_bf16 v[16:19], v[168:171], v[200:203], v[16:19]
	s_barrier
	s_add_u32 s66, s34, 0x80000
	s_addc_u32 s67, s35, 0
	s_add_i32 s68, s55, s43
	s_mov_b32 m0, s68
	s_nop 0
	global_load_lds_dwordx4 v138, s[66:67]
	s_add_i32 m0, s68, 0x2000
	s_nop 0
	global_load_lds_dwordx4 v134, s[66:67]
	s_waitcnt vmcnt(6)
	s_barrier
; #define PG8_STAGE(bufoff, gbase, voff) do { _Pragma("unroll") for (int _i = 0; _i < 2; ++_i) \
;         __builtin_amdgcn_global_load_lds((const unsigned*)((const char*)(gbase) + (voff)[_i]), (LAS unsigned*)(lds + (bufoff) + ldsw + _i * 8192), 16, 0, 0); } while (0)
; #define PG8_LDA(dst, b, h) do { _Pragma("unroll") for (int m = 0; m < 4; ++m) _Pragma("unroll") for (int k = 0; k < 2; ++k) dst[m][k] = *(const LAS bf16x8*)(lds + PG8_SA(b, h) + aoff + m * 2048 + k * 1024); } while (0)
; #define PG8_LDB(dst, b, h) do { _Pragma("unroll") for (int n = 0; n < 2; ++n) _Pragma("unroll") for (int k = 0; k < 2; ++k) dst[n][k] = *(const LAS bf16x8*)(lds + PG8_SB(b, h) + boff + n * 2048 + k * 1024); } while (0)
; #define PG8_MMA(ai, bj, At, Bt) do { __builtin_amdgcn_s_setprio(1); _Pragma("unroll") for (int m = 0; m < 4; ++m) _Pragma("unroll") for (int n = 0; n < 2; ++n) _Pragma("unroll") for (int k = 0; k < 2; ++k) \
;         acc[ai][bj][m][n] = __builtin_amdgcn_mfma_f32_16x16x32_bf16(Bt[n][k], At[m][k], acc[ai][bj][m][n], 0, 0, 0); __builtin_amdgcn_s_setprio(0); } while (0)
; #define PG8_WAIT_V(n) asm volatile("s_waitcnt vmcnt(" #n ")" ::: "memory")
; #define PG8_WAIT_L(n) asm volatile("s_waitcnt lgkmcnt(" #n ")" ::: "memory")
; #define PG8_BAR __builtin_amdgcn_s_barrier()
; #define PG8_SCHED __builtin_amdgcn_sched_barrier(0)
; template <class Epi>
; __device__ __forceinline__ void gemm_phase(LAS unsigned char* lds, const Gemm g, const StaticOrder& S, const Epi& E) {
;     ...
;             PG8_WAIT_V(6); PG8_BAR; PG8_MMA(1, 1, At, B1); PG8_BAR;
;             PG8_LDB(B0, 1, 0); PG8_SCHED; PG8_LDA(At, 1, 0); PG8_STAGE(PG8_SA(0, 1), a2 + hstep, voffA);
;             PG8_WAIT_L(8); PG8_BAR; PG8_WAIT_L(0); PG8_MMA(0, 0, At, B0); PG8_BAR; PG8_SCHED;
;             PG8_LDB(B1, 1, 1); PG8_STAGE(PG8_SB(1, 0), b3, voffB);
;             PG8_BAR; PG8_WAIT_L(0); PG8_MMA(0, 1, At, B1); PG8_BAR;
;             PG8_LDA(At, 1, 1); PG8_STAGE(PG8_SA(1, 0), a3, voffA);
;             PG8_BAR; PG8_WAIT_L(0); PG8_MMA(1, 0, At, B0); PG8_BAR; PG8_SCHED;
	v_mfma_f32_16x16x32_bf16 v[44:47], v[204:207], v[172:175], v[44:47]
	v_mfma_f32_16x16x32_bf16 v[40:43], v[212:215], v[172:175], v[40:43]
	v_mfma_f32_16x16x32_bf16 v[28:31], v[204:207], v[180:183], v[28:31]
	v_mfma_f32_16x16x32_bf16 v[24:27], v[212:215], v[180:183], v[24:27]
	v_mfma_f32_16x16x32_bf16 v[12:15], v[204:207], v[188:191], v[12:15]
	v_mfma_f32_16x16x32_bf16 v[8:11], v[212:215], v[188:191], v[8:11]
	v_mfma_f32_16x16x32_bf16 v[4:7], v[204:207], v[196:199], v[4:7]
	v_mfma_f32_16x16x32_bf16 v[0:3], v[212:215], v[196:199], v[0:3]
	v_mfma_f32_16x16x32_bf16 v[44:47], v[208:211], v[176:179], v[44:47]
	v_mfma_f32_16x16x32_bf16 v[40:43], v[216:219], v[176:179], v[40:43]
	v_mfma_f32_16x16x32_bf16 v[28:31], v[208:211], v[184:187], v[28:31]
	v_mfma_f32_16x16x32_bf16 v[24:27], v[216:219], v[184:187], v[24:27]
	v_mfma_f32_16x16x32_bf16 v[12:15], v[208:211], v[192:195], v[12:15]
	v_mfma_f32_16x16x32_bf16 v[8:11], v[216:219], v[192:195], v[8:11]
	v_mfma_f32_16x16x32_bf16 v[4:7], v[208:211], v[200:203], v[4:7]
	v_mfma_f32_16x16x32_bf16 v[0:3], v[216:219], v[200:203], v[0:3]
	s_add_i32 s66, 0, 0x18000
	s_barrier
	ds_read_b128 v[156:159], v220
	ds_read_b128 v[160:163], v220 offset:1024
	ds_read_b128 v[164:167], v220 offset:2048
	ds_read_b128 v[168:171], v220 offset:3072
	s_add_u32 s40, s40, 0x80000
	s_addc_u32 s41, s41, 0
	s_mov_b32 m0, s47
	ds_read_b128 v[172:175], v153 offset:32768
	ds_read_b128 v[176:179], v153 offset:33792
	ds_read_b128 v[180:183], v153 offset:34816
	ds_read_b128 v[184:187], v153 offset:35840
	ds_read_b128 v[188:191], v153 offset:36864
	ds_read_b128 v[192:195], v153 offset:37888
	ds_read_b128 v[196:199], v153 offset:38912
	ds_read_b128 v[200:203], v153 offset:39936
	global_load_lds_dwordx4 v140, s[40:41]
	s_mov_b32 m0, s48
	s_nop 0
	global_load_lds_dwordx4 v136, s[40:41]
	s_waitcnt lgkmcnt(8)
	s_barrier
	s_waitcnt lgkmcnt(0)
	v_mfma_f32_16x16x32_bf16 v[124:127], v[156:159], v[172:175], v[124:127]
	v_mfma_f32_16x16x32_bf16 v[120:123], v[164:167], v[172:175], v[120:123]
	v_mfma_f32_16x16x32_bf16 v[116:119], v[156:159], v[180:183], v[116:119]
	v_mfma_f32_16x16x32_bf16 v[112:115], v[164:167], v[180:183], v[112:115]
	v_mfma_f32_16x16x32_bf16 v[100:103], v[156:159], v[188:191], v[100:103]
	v_mfma_f32_16x16x32_bf16 v[96:99], v[164:167], v[188:191], v[96:99]
	v_mfma_f32_16x16x32_bf16 v[84:87], v[156:159], v[196:199], v[84:87]
	v_mfma_f32_16x16x32_bf16 v[80:83], v[164:167], v[196:199], v[80:83]
	v_mfma_f32_16x16x32_bf16 v[124:127], v[160:163], v[176:179], v[124:127]
	v_mfma_f32_16x16x32_bf16 v[120:123], v[168:171], v[176:179], v[120:123]
	v_mfma_f32_16x16x32_bf16 v[116:119], v[160:163], v[184:187], v[116:119]
	v_mfma_f32_16x16x32_bf16 v[112:115], v[168:171], v[184:187], v[112:115]
	v_mfma_f32_16x16x32_bf16 v[100:103], v[160:163], v[192:195], v[100:103]
	v_mfma_f32_16x16x32_bf16 v[96:99], v[168:171], v[192:195], v[96:99]
	v_mfma_f32_16x16x32_bf16 v[84:87], v[160:163], v[200:203], v[84:87]
	v_mfma_f32_16x16x32_bf16 v[80:83], v[168:171], v[200:203], v[80:83]
	s_barrier
	s_add_i32 s40, 0, 0x1c000
	s_add_i32 s41, s66, s43
	s_mov_b32 m0, s41
	ds_read_b128 v[204:207], v221
	ds_read_b128 v[208:211], v221 offset:1024
	ds_read_b128 v[212:215], v221 offset:2048
	ds_read_b128 v[216:219], v221 offset:3072
	global_load_lds_dwordx4 v138, s[72:73]
	s_add_i32 m0, s41, 0x2000
	s_nop 0
	global_load_lds_dwordx4 v134, s[72:73]
	s_barrier
	s_waitcnt lgkmcnt(0)
	v_mfma_f32_16x16x32_bf16 v[108:111], v[204:207], v[172:175], v[108:111]
	v_mfma_f32_16x16x32_bf16 v[104:107], v[212:215], v[172:175], v[104:107]
	v_mfma_f32_16x16x32_bf16 v[92:95], v[204:207], v[180:183], v[92:95]
	v_mfma_f32_16x16x32_bf16 v[88:91], v[212:215], v[180:183], v[88:91]
	v_mfma_f32_16x16x32_bf16 v[76:79], v[204:207], v[188:191], v[76:79]
	v_mfma_f32_16x16x32_bf16 v[72:75], v[212:215], v[188:191], v[72:75]
	v_mfma_f32_16x16x32_bf16 v[68:71], v[204:207], v[196:199], v[68:71]
	v_mfma_f32_16x16x32_bf16 v[64:67], v[212:215], v[196:199], v[64:67]
	v_mfma_f32_16x16x32_bf16 v[108:111], v[208:211], v[176:179], v[108:111]
	v_mfma_f32_16x16x32_bf16 v[104:107], v[216:219], v[176:179], v[104:107]
	v_mfma_f32_16x16x32_bf16 v[92:95], v[208:211], v[184:187], v[92:95]
	v_mfma_f32_16x16x32_bf16 v[88:91], v[216:219], v[184:187], v[88:91]
	v_mfma_f32_16x16x32_bf16 v[76:79], v[208:211], v[192:195], v[76:79]
	v_mfma_f32_16x16x32_bf16 v[72:75], v[216:219], v[192:195], v[72:75]
	v_mfma_f32_16x16x32_bf16 v[68:71], v[208:211], v[200:203], v[68:71]
	v_mfma_f32_16x16x32_bf16 v[64:67], v[216:219], v[200:203], v[64:67]
	s_mov_b32 m0, s50
	s_barrier
	ds_read_b128 v[172:175], v153 offset:49152
	ds_read_b128 v[176:179], v153 offset:50176
	ds_read_b128 v[180:183], v153 offset:51200
	ds_read_b128 v[184:187], v153 offset:52224
	ds_read_b128 v[188:191], v153 offset:53248
	ds_read_b128 v[192:195], v153 offset:54272
	ds_read_b128 v[196:199], v153 offset:55296
	ds_read_b128 v[200:203], v153 offset:56320
	global_load_lds_dwordx4 v140, s[74:75]
	s_mov_b32 m0, s51
	s_nop 0
	global_load_lds_dwordx4 v136, s[74:75]
	s_barrier
	s_waitcnt lgkmcnt(0)
	v_mfma_f32_16x16x32_bf16 v[60:63], v[156:159], v[172:175], v[60:63]
	v_mfma_f32_16x16x32_bf16 v[56:59], v[164:167], v[172:175], v[56:59]
	v_mfma_f32_16x16x32_bf16 v[52:55], v[156:159], v[180:183], v[52:55]
	v_mfma_f32_16x16x32_bf16 v[48:51], v[164:167], v[180:183], v[48:51]
	v_mfma_f32_16x16x32_bf16 v[36:39], v[156:159], v[188:191], v[36:39]
	v_mfma_f32_16x16x32_bf16 v[32:35], v[164:167], v[188:191], v[32:35]
	v_mfma_f32_16x16x32_bf16 v[20:23], v[156:159], v[196:199], v[20:23]
	v_mfma_f32_16x16x32_bf16 v[16:19], v[164:167], v[196:199], v[16:19]
	v_mfma_f32_16x16x32_bf16 v[60:63], v[160:163], v[176:179], v[60:63]
	v_mfma_f32_16x16x32_bf16 v[56:59], v[168:171], v[176:179], v[56:59]
	v_mfma_f32_16x16x32_bf16 v[52:55], v[160:163], v[184:187], v[52:55]
	v_mfma_f32_16x16x32_bf16 v[48:51], v[168:171], v[184:187], v[48:51]
	v_mfma_f32_16x16x32_bf16 v[36:39], v[160:163], v[192:195], v[36:39]
	v_mfma_f32_16x16x32_bf16 v[32:35], v[168:171], v[192:195], v[32:35]
	v_mfma_f32_16x16x32_bf16 v[20:23], v[160:163], v[200:203], v[20:23]
	v_mfma_f32_16x16x32_bf16 v[16:19], v[168:171], v[200:203], v[16:19]
	s_barrier
; __device__ __forceinline__ unsigned pk_bf16(float lo, float hi) { const f32x2 v = (f32x2){lo, hi}; const bf16v2 b = __builtin_convertvector(v, bf16v2); return __builtin_bit_cast(unsigned, b); }
; #define PG8_MMA(ai, bj, At, Bt) do { __builtin_amdgcn_s_setprio(1); _Pragma("unroll") for (int m = 0; m < 4; ++m) _Pragma("unroll") for (int n = 0; n < 2; ++n) _Pragma("unroll") for (int k = 0; k < 2; ++k) \
;         acc[ai][bj][m][n] = __builtin_amdgcn_mfma_f32_16x16x32_bf16(Bt[n][k], At[m][k], acc[ai][bj][m][n], 0, 0, 0); __builtin_amdgcn_s_setprio(0); } while (0)
; #define PG8_WAIT_V(n) asm volatile("s_waitcnt vmcnt(" #n ")" ::: "memory")
; #define PG8_BAR __builtin_amdgcn_s_barrier()
; template <class Epi>
; __device__ __forceinline__ void gemm_phase(LAS unsigned char* lds, const Gemm g, const StaticOrder& S, const Epi& E) {
;     ...
;             PG8_WAIT_V(6); PG8_BAR; PG8_MMA(1, 1, At, B1); PG8_BAR;
;         }
;         E(acc, cur, wr, wc, fr, fq);
;         if (!has_next) break;
; #pragma unroll
;         for (int a = 0; a < 2; ++a)
; #pragma unroll
;             for (int b = 0; b < 2; ++b)
; #pragma unroll
;                 for (int m = 0; m < 4; ++m)
; #pragma unroll
;                     for (int n = 0; n < 2; ++n) acc[a][b][m][n] = (f32x4){0.f, 0.f, 0.f, 0.f};
;         cur = nxt; cA = nA; cB = nB; ++ui;
;     }
;     PG8_WAIT_V(0);
;     if (wr == 0) PG8_BAR;
;     __device__ __forceinline__ void operator()(const f32x4 (&acc)[2][2][4][2], const pg8::Unit& u, int wr, int wc, int fr, int fq) const {
;         const int row0 = u.pm * 256 + wr * 64 + fr, col0 = u.pn * 256 + wc * 32 + 8 * fq;
; #pragma unroll
;         for (int ai = 0; ai < 2; ++ai)
; #pragma unroll
;             for (int m = 0; m < 4; ++m) {
;                 const int row = row0 + ai * 128 + m * 16;
;                 bf16_t* orow = yb + (size_t)row * DM + col0;
; #pragma unroll
;                 for (int bj = 0; bj < 2; ++bj) {
;                     const f32x4 v0 = acc[ai][bj][m][0], v1 = acc[ai][bj][m][1];
;                     *(u32x4*)(orow + bj * 128) = (u32x4){pk_bf16(v0[0], v0[1]), pk_bf16(v0[2], v0[3]), pk_bf16(v1[0], v1[1]), pk_bf16(v1[2], v1[3])};
;                 }
;             }
	s_add_u32 s34, s34, 0x80080
	s_addc_u32 s35, s35, 0
	s_add_i32 s40, s40, s43
	s_mov_b32 m0, s40
	s_nop 0
	global_load_lds_dwordx4 v138, s[34:35]
	s_add_i32 m0, s40, 0x2000
	s_nop 0
	global_load_lds_dwordx4 v134, s[34:35]
	s_waitcnt vmcnt(6)
	s_barrier
	v_mfma_f32_16x16x32_bf16 v[44:47], v[204:207], v[172:175], v[44:47]
	v_mfma_f32_16x16x32_bf16 v[40:43], v[212:215], v[172:175], v[40:43]
	v_mfma_f32_16x16x32_bf16 v[28:31], v[204:207], v[180:183], v[28:31]
	v_mfma_f32_16x16x32_bf16 v[24:27], v[212:215], v[180:183], v[24:27]
	v_mfma_f32_16x16x32_bf16 v[12:15], v[204:207], v[188:191], v[12:15]
	v_mfma_f32_16x16x32_bf16 v[8:11], v[212:215], v[188:191], v[8:11]
	v_mfma_f32_16x16x32_bf16 v[4:7], v[204:207], v[196:199], v[4:7]
	v_mfma_f32_16x16x32_bf16 v[0:3], v[212:215], v[196:199], v[0:3]
	v_mfma_f32_16x16x32_bf16 v[44:47], v[208:211], v[176:179], v[44:47]
	v_mfma_f32_16x16x32_bf16 v[40:43], v[216:219], v[176:179], v[40:43]
	v_mfma_f32_16x16x32_bf16 v[28:31], v[208:211], v[184:187], v[28:31]
	v_mfma_f32_16x16x32_bf16 v[24:27], v[216:219], v[184:187], v[24:27]
	v_mfma_f32_16x16x32_bf16 v[12:15], v[208:211], v[192:195], v[12:15]
	v_mfma_f32_16x16x32_bf16 v[8:11], v[216:219], v[192:195], v[8:11]
	v_mfma_f32_16x16x32_bf16 v[4:7], v[208:211], v[200:203], v[4:7]
	v_mfma_f32_16x16x32_bf16 v[0:3], v[216:219], v[200:203], v[0:3]
	s_add_i32 s65, s65, 2
	s_add_u32 s30, s30, 0x100
	s_addc_u32 s31, s31, 0
	s_add_u32 s63, s63, 0x100
	s_addc_u32 s64, s64, 0
	s_cmp_gt_u32 s65, 29
	s_barrier
	s_cbranch_scc0 .LBB0_559
	v_lshl_add_u32 v156, s20, 8, v150
	v_lshl_or_b32 v158, s60, 8, v152
	v_ashrrev_i32_e32 v157, 31, v156
	v_ashrrev_i32_e32 v159, 31, v158
	v_lshlrev_b64 v[160:161], 12, v[156:157]
	v_lshl_add_u64 v[160:161], s[6:7], 0, v[160:161]
	v_lshlrev_b64 v[158:159], 1, v[158:159]
	v_lshl_add_u64 v[160:161], v[160:161], 0, v[158:159]
	v_cvt_pk_bf16_f32 v60, v60, v61
	v_cvt_pk_bf16_f32 v61, v62, v63
	v_cvt_pk_bf16_f32 v62, v56, v57
	v_add_co_u32_e32 v56, vcc, s56, v160
	v_cvt_pk_bf16_f32 v68, v68, v69
	v_cvt_pk_bf16_f32 v69, v70, v71
	v_cvt_pk_bf16_f32 v70, v64, v65
	v_lshl_add_u64 v[64:65], v[160:161], 0, s[10:11]
	v_addc_co_u32_e32 v57, vcc, 0, v161, vcc
	v_cvt_pk_bf16_f32 v44, v44, v45
	v_cvt_pk_bf16_f32 v45, v46, v47
	v_cvt_pk_bf16_f32 v46, v40, v41
	v_cvt_pk_bf16_f32 v47, v42, v43
	v_cvt_pk_bf16_f32 v108, v108, v109
	v_cvt_pk_bf16_f32 v109, v110, v111
	v_cvt_pk_bf16_f32 v110, v104, v105
	v_or_b32_e32 v104, 16, v156
	global_store_dwordx4 v[64:65], v[44:47], off offset:256
	v_ashrrev_i32_e32 v105, 31, v104
	v_cvt_pk_bf16_f32 v92, v92, v93
	v_add_co_u32_e32 v46, vcc, s57, v160
	v_cvt_pk_bf16_f32 v93, v94, v95
	v_cvt_pk_bf16_f32 v94, v88, v89
	v_or_b32_e32 v88, 32, v156
	v_lshl_add_u64 v[44:45], v[160:161], 0, s[14:15]
	v_addc_co_u32_e32 v47, vcc, 0, v161, vcc
	v_cvt_pk_bf16_f32 v28, v28, v29
	v_cvt_pk_bf16_f32 v29, v30, v31
	v_cvt_pk_bf16_f32 v30, v24, v25
	v_cvt_pk_bf16_f32 v31, v26, v27
	v_lshlrev_b64 v[104:105], 12, v[104:105]
	v_ashrrev_i32_e32 v89, 31, v88
	v_cvt_pk_bf16_f32 v76, v76, v77
	v_cvt_pk_bf16_f32 v77, v78, v79
	v_cvt_pk_bf16_f32 v78, v72, v73
	v_or_b32_e32 v72, 48, v156
	global_store_dwordx4 v[44:45], v[28:31], off offset:256
	v_cvt_pk_bf16_f32 v111, v106, v107
	v_lshl_add_u64 v[104:105], s[6:7], 0, v[104:105]
	v_add_co_u32_e32 v30, vcc, s58, v160
	v_lshlrev_b64 v[88:89], 12, v[88:89]
	v_ashrrev_i32_e32 v73, 31, v72
	v_lshl_add_u64 v[28:29], v[160:161], 0, s[16:17]
	v_addc_co_u32_e32 v31, vcc, 0, v161, vcc
	v_cvt_pk_bf16_f32 v12, v12, v13
	v_cvt_pk_bf16_f32 v13, v14, v15
	v_cvt_pk_bf16_f32 v14, v8, v9
	v_cvt_pk_bf16_f32 v15, v10, v11
	global_store_dwordx4 v[160:161], v[108:111], off offset:256
	v_cvt_pk_bf16_f32 v95, v90, v91
	v_lshl_add_u64 v[88:89], s[6:7], 0, v[88:89]
	v_lshl_add_u64 v[108:109], v[104:105], 0, v[158:159]
	v_lshlrev_b64 v[72:73], 12, v[72:73]
	global_store_dwordx4 v[28:29], v[12:15], off offset:256
	global_store_dwordx4 v[108:109], v[92:95], off offset:256
	v_cvt_pk_bf16_f32 v79, v74, v75
	v_add_co_u32_e32 v14, vcc, s59, v160
	v_lshl_add_u64 v[92:93], v[88:89], 0, v[158:159]
	v_lshl_add_u64 v[72:73], s[6:7], 0, v[72:73]
	v_addc_co_u32_e32 v15, vcc, 0, v161, vcc
	v_cvt_pk_bf16_f32 v124, v124, v125
	v_cvt_pk_bf16_f32 v125, v126, v127
	v_cvt_pk_bf16_f32 v126, v120, v121
	v_cvt_pk_bf16_f32 v127, v122, v123
	v_cvt_pk_bf16_f32 v104, v116, v117
	v_cvt_pk_bf16_f32 v105, v118, v119
	v_cvt_pk_bf16_f32 v106, v112, v113
	v_cvt_pk_bf16_f32 v107, v114, v115
	v_cvt_pk_bf16_f32 v88, v100, v101
	v_cvt_pk_bf16_f32 v89, v102, v103
	v_cvt_pk_bf16_f32 v90, v96, v97
	v_cvt_pk_bf16_f32 v91, v98, v99
	global_store_dwordx4 v[92:93], v[76:79], off offset:256
	v_cvt_pk_bf16_f32 v74, v80, v81
	v_cvt_pk_bf16_f32 v75, v82, v83
	v_lshl_add_u64 v[76:77], v[72:73], 0, v[158:159]
	v_cvt_pk_bf16_f32 v72, v84, v85
	v_cvt_pk_bf16_f32 v73, v86, v87
	v_cvt_pk_bf16_f32 v71, v66, v67
	v_cvt_pk_bf16_f32 v63, v58, v59
	v_cvt_pk_bf16_f32 v40, v52, v53
	v_cvt_pk_bf16_f32 v41, v54, v55
	v_cvt_pk_bf16_f32 v42, v48, v49
	v_cvt_pk_bf16_f32 v43, v50, v51
	v_cvt_pk_bf16_f32 v24, v36, v37
	v_cvt_pk_bf16_f32 v25, v38, v39
	v_cvt_pk_bf16_f32 v26, v32, v33
	v_cvt_pk_bf16_f32 v27, v34, v35
	v_lshl_add_u64 v[12:13], v[160:161], 0, s[18:19]
	v_cvt_pk_bf16_f32 v8, v20, v21
	v_cvt_pk_bf16_f32 v9, v22, v23
	v_cvt_pk_bf16_f32 v10, v16, v17
	v_cvt_pk_bf16_f32 v11, v18, v19
	v_cvt_pk_bf16_f32 v4, v4, v5
	v_cvt_pk_bf16_f32 v5, v6, v7
	v_cvt_pk_bf16_f32 v6, v0, v1
	v_cvt_pk_bf16_f32 v7, v2, v3
	s_and_b64 vcc, exec, s[8:9]
	s_mov_b32 s60, s22
	s_mov_b32 s20, s24
	s_mov_b64 s[34:35], s[28:29]
	s_mov_b64 s[30:31], s[26:27]
	s_mov_b32 s40, s70
	global_store_dwordx4 v[160:161], v[124:127], off
	global_store_dwordx4 v[108:109], v[104:107], off
	global_store_dwordx4 v[92:93], v[88:91], off
	global_store_dwordx4 v[76:77], v[72:75], off
	global_store_dwordx4 v[76:77], v[68:71], off offset:256
	global_store_dwordx4 v[56:57], v[60:63], off
	global_store_dwordx4 v[46:47], v[40:43], off
	global_store_dwordx4 v[30:31], v[24:27], off
	global_store_dwordx4 v[14:15], v[8:11], off
	global_store_dwordx4 v[12:13], v[4:7], off offset:256
	s_cbranch_vccnz .Lg2_exit
	s_cmp_lg_u32 s49, 4
	s_cbranch_scc1 .LBB0_556
	s_waitcnt vmcnt(0)
	s_barrier
	s_lshr_b32 s8, s42, 6
	s_cmp_lg_u32 s8, 4
	s_cbranch_scc1 .LBB0_556
	buffer_wbl2 sc1
	s_waitcnt vmcnt(0)
	s_mov_b64 s[8:9], exec
	s_mov_b64 exec, 1
	v_mov_b32_e32 v0, 0
	v_mov_b32_e32 v1, 1
	global_atomic_add v0, v1, s[36:37] offset:256
	s_mov_b64 exec, s[8:9]
	s_branch .LBB0_556
